# P4: importance Q fragments requested one head ahead; hoisted Q loads waited for at first use
# speedup vs baseline: 1.0108x; 1.0018x over previous
.LBB0_686:
	s_nop 0
	v_div_scale_f32 v3, s[0:1], v4, v4, 1.0
	v_rcp_f32_e32 v6, v3
	v_div_scale_f32 v7, vcc, 1.0, v4, 1.0
	v_fma_f32 v8, -v3, v6, 1.0
	v_fmac_f32_e32 v6, v8, v6
	v_mul_f32_e32 v8, v7, v6
	v_fma_f32 v9, -v3, v8, v7
	v_fmac_f32_e32 v8, v9, v6
	v_fma_f32 v3, -v3, v8, v7
	v_div_fmas_f32 v3, v3, v6, v8
	v_div_scale_f32 v6, s[0:1], v5, v5, 1.0
	v_rcp_f32_e32 v7, v6
	v_div_fixup_f32 v3, v3, v4, 1.0
	v_cmp_lt_f32_e32 vcc, 0, v4
	s_nop 1
	v_cndmask_b32_e32 v3, 0, v3, vcc
	s_cmp_eq_u32 s11, 2
	s_cbranch_scc1 .Lgw8
	s_waitcnt vmcnt(0)
	s_branch .Lgw1
.Lgw8:
	s_waitcnt vmcnt(8)
.Lgw1:
	v_mul_f32_e32 v4, v210, v3
	v_fma_f32 v3, -v6, v7, 1.0
	v_fmac_f32_e32 v7, v3, v7
	v_div_scale_f32 v3, vcc, 1.0, v5, 1.0
	v_mul_f32_e32 v8, v3, v7
	v_fma_f32 v9, -v6, v8, v3
	v_fmac_f32_e32 v8, v9, v7
	v_fma_f32 v3, -v6, v8, v3
	v_div_fmas_f32 v3, v3, v7, v8
	v_div_fixup_f32 v3, v3, v5, 1.0
	v_cmp_lt_f32_e32 vcc, 0, v5
	v_pk_mul_f32 v[88:89], v[20:21], v[4:5] op_sel_hi:[1,0]
	v_pk_mul_f32 v[84:85], v[36:37], v[4:5] op_sel_hi:[1,0]
	v_cndmask_b32_e32 v3, 0, v3, vcc
	v_mul_f32_e32 v6, v211, v3
	v_pk_mul_f32 v[90:91], v[68:69], v[6:7] op_sel_hi:[1,0]
	v_pk_mul_f32 v[68:69], v[52:53], v[6:7] op_sel_hi:[1,0]
	v_pk_mul_f32 v[92:93], v[22:23], v[4:5] op_sel_hi:[1,0]
	v_pk_mul_f32 v[86:87], v[38:39], v[4:5] op_sel_hi:[1,0]
	v_pk_mul_f32 v[96:97], v[70:71], v[6:7] op_sel_hi:[1,0]
	v_pk_mul_f32 v[54:55], v[54:55], v[6:7] op_sel_hi:[1,0]
	v_pk_mul_f32 v[98:99], v[24:25], v[4:5] op_sel_hi:[1,0]
	v_pk_mul_f32 v[70:71], v[40:41], v[4:5] op_sel_hi:[1,0]
	v_pk_mul_f32 v[100:101], v[72:73], v[6:7] op_sel_hi:[1,0]
	v_pk_mul_f32 v[56:57], v[56:57], v[6:7] op_sel_hi:[1,0]
	v_pk_mul_f32 v[102:103], v[26:27], v[4:5] op_sel_hi:[1,0]
	v_pk_mul_f32 v[72:73], v[42:43], v[4:5] op_sel_hi:[1,0]
	v_pk_mul_f32 v[104:105], v[74:75], v[6:7] op_sel_hi:[1,0]
	v_pk_mul_f32 v[58:59], v[58:59], v[6:7] op_sel_hi:[1,0]
	v_pk_mul_f32 v[94:95], v[28:29], v[4:5] op_sel_hi:[1,0]
	v_pk_mul_f32 v[52:53], v[44:45], v[4:5] op_sel_hi:[1,0]
	v_pk_mul_f32 v[74:75], v[76:77], v[6:7] op_sel_hi:[1,0]
	v_pk_mul_f32 v[16:17], v[60:61], v[6:7] op_sel_hi:[1,0]
	v_pk_mul_f32 v[76:77], v[30:31], v[4:5] op_sel_hi:[1,0]
	v_pk_mul_f32 v[46:47], v[46:47], v[4:5] op_sel_hi:[1,0]
	v_pk_mul_f32 v[60:61], v[78:79], v[6:7] op_sel_hi:[1,0]
	v_pk_mul_f32 v[40:41], v[62:63], v[6:7] op_sel_hi:[1,0]
	v_pk_mul_f32 v[78:79], v[32:33], v[4:5] op_sel_hi:[1,0]
	v_pk_mul_f32 v[48:49], v[48:49], v[4:5] op_sel_hi:[1,0]
	v_pk_mul_f32 v[62:63], v[80:81], v[6:7] op_sel_hi:[1,0]
	v_pk_mul_f32 v[42:43], v[64:65], v[6:7] op_sel_hi:[1,0]
	v_pk_mul_f32 v[80:81], v[34:35], v[4:5] op_sel_hi:[1,0]
	v_pk_mul_f32 v[50:51], v[50:51], v[4:5] op_sel_hi:[1,0]
	v_pk_mul_f32 v[64:65], v[82:83], v[6:7] op_sel_hi:[1,0]
	s_andn2_b64 vcc, exec, s[24:25]
	v_pk_mul_f32 v[44:45], v[66:67], v[6:7] op_sel_hi:[1,0]
	s_cbranch_vccnz .LBB0_688
	ds_read_b128 v[12:15], v193
	ds_read_b128 v[20:23], v193 offset:2048
	ds_read_b128 v[8:11], v193 offset:4096
	ds_read_b128 v[4:7], v193 offset:6144
	ds_read_b128 v[24:27], v193 offset:1024
	s_waitcnt lgkmcnt(0)
	v_lshlrev_b32_e32 v28, 16, v12
	v_and_b32_e32 v29, 0xffff0000, v12
	v_pk_add_f32 v[88:89], v[88:89], v[28:29]
	v_lshlrev_b32_e32 v28, 16, v20
	v_and_b32_e32 v29, 0xffff0000, v20
	v_lshlrev_b32_e32 v12, 16, v13
	v_and_b32_e32 v13, 0xffff0000, v13
	v_pk_add_f32 v[84:85], v[84:85], v[28:29]
	v_lshlrev_b32_e32 v28, 16, v8
	v_and_b32_e32 v29, 0xffff0000, v8
	v_pk_add_f32 v[92:93], v[92:93], v[12:13]
	v_lshlrev_b32_e32 v12, 16, v14
	v_and_b32_e32 v13, 0xffff0000, v14
	v_pk_add_f32 v[90:91], v[90:91], v[28:29]
	v_lshlrev_b32_e32 v28, 16, v4
	v_and_b32_e32 v29, 0xffff0000, v4
	v_lshlrev_b32_e32 v4, 16, v5
	v_and_b32_e32 v5, 0xffff0000, v5
	v_pk_add_f32 v[98:99], v[98:99], v[12:13]
	v_lshlrev_b32_e32 v12, 16, v15
	v_and_b32_e32 v13, 0xffff0000, v15
	v_pk_add_f32 v[54:55], v[54:55], v[4:5]
	v_lshlrev_b32_e32 v4, 16, v6
	v_and_b32_e32 v5, 0xffff0000, v6
	v_pk_add_f32 v[102:103], v[102:103], v[12:13]
	ds_read_b128 v[12:15], v193 offset:3072
	v_lshlrev_b32_e32 v20, 16, v21
	v_and_b32_e32 v21, 0xffff0000, v21
	v_pk_add_f32 v[56:57], v[56:57], v[4:5]
	v_lshlrev_b32_e32 v4, 16, v7
	v_and_b32_e32 v5, 0xffff0000, v7
	v_pk_add_f32 v[86:87], v[86:87], v[20:21]
	v_lshlrev_b32_e32 v20, 16, v22
	v_and_b32_e32 v21, 0xffff0000, v22
	v_pk_add_f32 v[58:59], v[58:59], v[4:5]
	v_lshlrev_b32_e32 v4, 16, v24
	v_and_b32_e32 v5, 0xffff0000, v24
	v_pk_add_f32 v[70:71], v[70:71], v[20:21]
	v_lshlrev_b32_e32 v20, 16, v23
	v_and_b32_e32 v21, 0xffff0000, v23
	v_pk_add_f32 v[94:95], v[94:95], v[4:5]
	v_lshlrev_b32_e32 v4, 16, v25
	v_and_b32_e32 v5, 0xffff0000, v25
	v_pk_add_f32 v[72:73], v[72:73], v[20:21]
	ds_read_b128 v[20:23], v193 offset:5120
	v_pk_add_f32 v[76:77], v[76:77], v[4:5]
	v_lshlrev_b32_e32 v4, 16, v26
	v_and_b32_e32 v5, 0xffff0000, v26
	v_lshlrev_b32_e32 v8, 16, v9
	v_and_b32_e32 v9, 0xffff0000, v9
	v_pk_add_f32 v[78:79], v[78:79], v[4:5]
	v_lshlrev_b32_e32 v4, 16, v27
	v_and_b32_e32 v5, 0xffff0000, v27
	v_pk_add_f32 v[96:97], v[96:97], v[8:9]
	v_lshlrev_b32_e32 v8, 16, v10
	v_and_b32_e32 v9, 0xffff0000, v10
	v_pk_add_f32 v[80:81], v[80:81], v[4:5]
	s_waitcnt lgkmcnt(1)
	v_lshlrev_b32_e32 v4, 16, v12
	v_and_b32_e32 v5, 0xffff0000, v12
	v_pk_add_f32 v[100:101], v[100:101], v[8:9]
	v_lshlrev_b32_e32 v8, 16, v11
	v_and_b32_e32 v9, 0xffff0000, v11
	v_pk_add_f32 v[52:53], v[52:53], v[4:5]
	v_lshlrev_b32_e32 v4, 16, v13
	v_and_b32_e32 v5, 0xffff0000, v13
	v_pk_add_f32 v[104:105], v[104:105], v[8:9]
	ds_read_b128 v[8:11], v193 offset:7168
	v_pk_add_f32 v[46:47], v[46:47], v[4:5]
	v_lshlrev_b32_e32 v4, 16, v14
	v_and_b32_e32 v5, 0xffff0000, v14
	v_pk_add_f32 v[48:49], v[48:49], v[4:5]
	s_waitcnt lgkmcnt(1)
	v_lshlrev_b32_e32 v4, 16, v20
	v_and_b32_e32 v5, 0xffff0000, v20
	v_pk_add_f32 v[74:75], v[74:75], v[4:5]
	v_lshlrev_b32_e32 v4, 16, v21
	v_and_b32_e32 v5, 0xffff0000, v21
	v_pk_add_f32 v[60:61], v[60:61], v[4:5]
	v_lshlrev_b32_e32 v4, 16, v22
	v_and_b32_e32 v5, 0xffff0000, v22
	v_pk_add_f32 v[62:63], v[62:63], v[4:5]
	v_lshlrev_b32_e32 v4, 16, v23
	v_and_b32_e32 v5, 0xffff0000, v23
	v_pk_add_f32 v[64:65], v[64:65], v[4:5]
	s_waitcnt lgkmcnt(0)
	v_lshlrev_b32_e32 v4, 16, v8
	v_and_b32_e32 v5, 0xffff0000, v8
	v_pk_add_f32 v[16:17], v[16:17], v[4:5]
	v_lshlrev_b32_e32 v4, 16, v9
	v_and_b32_e32 v5, 0xffff0000, v9
	v_lshlrev_b32_e32 v3, 16, v15
	v_pk_add_f32 v[40:41], v[40:41], v[4:5]
	v_lshlrev_b32_e32 v4, 16, v10
	v_and_b32_e32 v5, 0xffff0000, v10
	v_add_f32_e32 v50, v50, v3
	v_and_b32_e32 v3, 0xffff0000, v15
	v_pk_add_f32 v[42:43], v[42:43], v[4:5]
	v_lshlrev_b32_e32 v4, 16, v11
	v_and_b32_e32 v5, 0xffff0000, v11
	v_pk_add_f32 v[68:69], v[68:69], v[28:29]
	v_add_f32_e32 v51, v51, v3
	v_pk_add_f32 v[44:45], v[44:45], v[4:5]
